# mixer D: relative-position-bias staging loop unrolled with its 8 loads in flight together
# speedup vs baseline: 1.0044x; 1.0041x over previous
; #define LAS __attribute__((address_space(3)))
; DI float d_stage_rpb(const float* rpb_l, int h, LAS char* vt, int lane) {
;     LAS float* rp = (LAS float*)(vt + 12288); float rmax = 0.f;
;     for (int i = lane; i < 15 * 31; i += 64) { const float v = rpb_l[h * 465 + i] * LOG2E; rp[i] = v; rmax = fmaxf(rmax, fabsf(v)); }
; #pragma unroll
;     for (int o_ = 1; o_ < 64; o_ <<= 1) rmax = fmaxf(rmax, __shfl_xor(rmax, o_));
;     return rmax;
; }
; __global__ void __launch_bounds__(512) fwd_kernel(Args a) {
;     ...
;                 int hcur = -1; float rmax = 0.f;
;                 for (int u = blockIdx.x; u < 512; u += G) { const int hd = (u >> 4) & 3; if (hd != hcur) { rmax = d_stage_rpb(a.in[14] + l * 4 * 15 * 31, hd, vt, lane); hcur = hd; }
.LBB0_364:
	s_bfe_u32 s53, s52, 0x20004
	s_cmp_eq_u32 s53, s34
	s_cbranch_scc1 .LBB0_363
	s_lshr_b32 s0, s52, 4
	s_and_b32 s0, s0, 3
	s_mulk_i32 s0, 0x1d1
	v_add_lshl_u32 v188, v69, s0, 2
	v_lshl_add_u64 v[4:5], s[20:21], 0, v[188:189]
	v_mov_b32_e32 v8, 0
	s_movk_i32 s26, 0x190
	global_load_dword v9, v[4:5], off
	global_load_dword v10, v[4:5], off offset:256
	global_load_dword v11, v[4:5], off offset:512
	global_load_dword v12, v[4:5], off offset:768
	global_load_dword v13, v[4:5], off offset:1024
	global_load_dword v14, v[4:5], off offset:1280
	global_load_dword v15, v[4:5], off offset:1536
	v_cmp_gt_u32_e32 vcc, 17, v69
	s_and_saveexec_b64 s[0:1], vcc
	global_load_dword v16, v[4:5], off offset:1792
	s_or_b64 exec, exec, s[0:1]
	s_waitcnt vmcnt(7)
	v_mul_f32_e32 v9, 0x3fb8aa3b, v9
	ds_write_b32 v93, v9
	v_max_f32_e64 v8, v8, |v9|
	s_waitcnt vmcnt(6)
	v_mul_f32_e32 v10, 0x3fb8aa3b, v10
	ds_write_b32 v93, v10 offset:256
	v_max_f32_e64 v8, v8, |v10|
	s_waitcnt vmcnt(5)
	v_mul_f32_e32 v11, 0x3fb8aa3b, v11
	ds_write_b32 v93, v11 offset:512
	v_max_f32_e64 v8, v8, |v11|
	s_waitcnt vmcnt(4)
	v_mul_f32_e32 v12, 0x3fb8aa3b, v12
	ds_write_b32 v93, v12 offset:768
	v_max_f32_e64 v8, v8, |v12|
	s_waitcnt vmcnt(3)
	v_mul_f32_e32 v13, 0x3fb8aa3b, v13
	ds_write_b32 v93, v13 offset:1024
	v_max_f32_e64 v8, v8, |v13|
	s_waitcnt vmcnt(2)
	v_mul_f32_e32 v14, 0x3fb8aa3b, v14
	ds_write_b32 v93, v14 offset:1280
	v_max_f32_e64 v8, v8, |v14|
	s_waitcnt vmcnt(1)
	v_mul_f32_e32 v15, 0x3fb8aa3b, v15
	ds_write_b32 v93, v15 offset:1536
	v_max_f32_e64 v8, v8, |v15|
	s_and_saveexec_b64 s[0:1], vcc
	s_waitcnt vmcnt(0)
	v_mul_f32_e32 v16, 0x3fb8aa3b, v16
	ds_write_b32 v93, v16 offset:1792
	v_max_f32_e64 v8, v8, |v16|
	s_or_b64 exec, exec, s[0:1]
	ds_bpermute_b32 v4, v89, v8
	v_max_f32_e32 v5, v8, v8
	s_mov_b32 s34, s53
	s_waitcnt lgkmcnt(0)
	v_max_f32_e32 v4, v4, v4
	v_max_f32_e32 v4, v5, v4
	ds_bpermute_b32 v5, v90, v4
	s_waitcnt lgkmcnt(0)
	v_max_f32_e32 v5, v5, v5
	v_max_f32_e32 v4, v4, v5
	ds_bpermute_b32 v5, v91, v4
	s_waitcnt lgkmcnt(0)
	v_max_f32_e32 v5, v5, v5
	v_max_f32_e32 v4, v4, v5
	ds_bpermute_b32 v5, v92, v4
	s_waitcnt lgkmcnt(0)
	v_max_f32_e32 v5, v5, v5
	v_max_f32_e32 v4, v4, v5
	ds_bpermute_b32 v5, v79, v4
	s_waitcnt lgkmcnt(0)
	v_max_f32_e32 v5, v5, v5
	v_max_f32_e32 v4, v4, v5
	ds_bpermute_b32 v5, v80, v4
	s_waitcnt lgkmcnt(0)
	v_max_f32_e32 v5, v5, v5
	v_max_f32_e32 v99, v4, v5
	s_branch .LBB0_363
